# L5b token loop: cross-token prefetch of the 6 row loads into a second register set (on top of v50)
# baseline (speedup 1.0000x reference)
.LBB0_1728:
	s_or_b64 exec, exec, s[4:5]
	s_mov_b64 s[4:5], s[0:1]
	s_mov_b64 s[10:11], s[0:1]
	v_mov_b32_e32 v1, v205
	s_mov_b32 s2, s61
	s_waitcnt lgkmcnt(0)
	v_mov_b32_e32 v0, v205
	s_barrier
	s_lshl_b32 s8, s2, 2
	v_ashrrev_i32_e32 v0, 6, v0
	v_add_u32_e32 v30, s8, v0
	s_movk_i32 s2, 0x5000
	v_cmp_gt_i32_e32 vcc, s2, v30
	s_and_saveexec_b64 s[6:7], vcc
	s_cbranch_execz .LBB0_1733
	v_and_b32_e32 v4, 63, v1
	v_and_b32_e32 v1, 64, v216
	v_add_u32_e32 v1, 64, v1
	v_xor_b32_e32 v2, 1, v216
	v_cmp_lt_i32_e32 vcc, v2, v1
	s_load_dwordx2 s[12:13], s[4:5], 0x108
	s_nop 0
	s_load_dwordx2 s[10:11], s[10:11], 0x108
	v_cndmask_b32_e32 v2, v216, v2, vcc
	v_lshlrev_b32_e32 v31, 2, v2
	v_xor_b32_e32 v2, 2, v216
	v_cmp_lt_i32_e32 vcc, v2, v1
	s_ashr_i32 s9, s8, 31
	v_cmp_eq_u32_e64 s[4:5], 0, v4
	v_cndmask_b32_e32 v2, v216, v2, vcc
	v_lshlrev_b32_e32 v32, 2, v2
	v_xor_b32_e32 v2, 4, v216
	v_cmp_lt_i32_e32 vcc, v2, v1
	s_nop 1
	v_cndmask_b32_e32 v2, v216, v2, vcc
	v_lshlrev_b32_e32 v33, 2, v2
	v_xor_b32_e32 v2, 8, v216
	v_cmp_lt_i32_e32 vcc, v2, v1
	s_nop 1
	v_cndmask_b32_e32 v2, v216, v2, vcc
	v_lshlrev_b32_e32 v34, 2, v2
	v_xor_b32_e32 v2, 16, v216
	v_cmp_lt_i32_e32 vcc, v2, v1
	s_nop 1
	v_cndmask_b32_e32 v2, v216, v2, vcc
	v_lshlrev_b32_e32 v35, 2, v2
	v_xor_b32_e32 v2, 32, v216
	v_cmp_lt_i32_e32 vcc, v2, v1
	s_nop 1
	v_cndmask_b32_e32 v1, v216, v2, vcc
	v_lshlrev_b32_e32 v36, 2, v1
	v_ashrrev_i32_e32 v1, 31, v0
	v_lshl_add_u64 v[0:1], v[0:1], 0, s[8:9]
	s_waitcnt lgkmcnt(0)
	v_lshl_add_u64 v[2:3], v[0:1], 2, s[10:11]
	s_mov_b64 s[8:9], 0x1d4d4000
	v_lshl_add_u64 v[12:13], v[2:3], 0, s[8:9]
	v_lshlrev_b32_e32 v2, 4, v4
	v_mov_b32_e32 v3, v129
	v_mad_u64_u32 v[2:3], s[8:9], v0, s33, v[2:3]
	v_mad_i32_i24 v3, v1, s33, v3
	v_lshl_add_u64 v[0:1], s[12:13], 0, v[2:3]
	s_mov_b64 s[8:9], 0x26a0000
	v_lshl_add_u64 v[14:15], v[0:1], 0, s[8:9]
	s_mov_b64 s[8:9], 0
	v_add_co_u32_e32 v168, vcc, 0x1000, v14
	s_nop 1
	v_addc_co_u32_e32 v169, vcc, 0, v15, vcc
	global_load_dwordx4 v[142:145], v[168:169], off offset:1024
	global_load_dwordx4 v[146:149], v[14:15], off
	global_load_dwordx4 v[150:153], v[14:15], off offset:3072
	global_load_dwordx4 v[154:157], v[168:169], off offset:2048
	global_load_dwordx4 v[158:161], v[14:15], off offset:1024
	global_load_dwordx4 v[162:165], v[168:169], off
	s_waitcnt vmcnt(0)
	s_branch .LBB0_1731
.LBB0_1730:
	s_waitcnt vmcnt(2)
	s_or_b64 exec, exec, s[10:11]
	v_add_u32_e32 v30, s66, v30
	v_readlane_b32 s10, v252, 28
	v_readlane_b32 s11, v252, 29
	v_cmp_lt_i32_e32 vcc, s84, v30
	s_or_b64 s[8:9], vcc, s[8:9]
	v_lshl_add_u64 v[12:13], v[12:13], 0, s[10:11]
	v_lshl_add_u64 v[14:15], v[14:15], 0, s[70:71]
	s_andn2_b64 exec, exec, s[8:9]
	s_cbranch_execz .LBB0_1733
.LBB0_1731:
	v_add_co_u32_e32 v16, vcc, 0x1000, v14
	s_nop 1
	s_nop 0
	v_addc_co_u32_e32 v17, vcc, 0, v15, vcc
	s_waitcnt lgkmcnt(0)
	v_mov_b32_e32 v0, v142
	v_mov_b32_e32 v1, v143
	v_mov_b32_e32 v2, v144
	v_mov_b32_e32 v3, v145
	v_mov_b32_e32 v4, v146
	v_mov_b32_e32 v5, v147
	v_mov_b32_e32 v6, v148
	v_mov_b32_e32 v7, v149
	v_mov_b32_e32 v8, v150
	v_mov_b32_e32 v9, v151
	v_mov_b32_e32 v10, v152
	v_mov_b32_e32 v11, v153
	v_mov_b32_e32 v130, v154
	v_mov_b32_e32 v131, v155
	v_mov_b32_e32 v132, v156
	v_mov_b32_e32 v133, v157
	v_mov_b32_e32 v134, v158
	v_mov_b32_e32 v135, v159
	v_mov_b32_e32 v136, v160
	v_mov_b32_e32 v137, v161
	v_mov_b32_e32 v138, v162
	v_mov_b32_e32 v139, v163
	v_mov_b32_e32 v140, v164
	v_mov_b32_e32 v141, v165
	v_lshl_add_u64 v[166:167], v[14:15], 0, s[70:71]
	v_add_co_u32_e32 v168, vcc, 0x1000, v166
	s_nop 1
	v_addc_co_u32_e32 v169, vcc, 0, v167, vcc
	global_load_dwordx4 v[142:145], v[168:169], off offset:1024
	global_load_dwordx4 v[146:149], v[166:167], off
	global_load_dwordx4 v[150:153], v[166:167], off offset:3072
	global_load_dwordx4 v[154:157], v[168:169], off offset:2048
	global_load_dwordx4 v[158:161], v[166:167], off offset:1024
	global_load_dwordx4 v[162:165], v[168:169], off
	v_lshlrev_b32_e32 v18, 16, v0
	v_and_b32_e32 v19, 0xffff0000, v0
	v_lshlrev_b32_e32 v0, 16, v8
	v_lshlrev_b32_e32 v20, 16, v4
	v_and_b32_e32 v21, 0xffff0000, v4
	v_and_b32_e32 v4, 0xffff0000, v8
	v_mul_f32_e32 v8, 0xbfb8aa3b, v0
	v_exp_f32_e32 v22, v8
	v_mul_f32_e32 v8, 0xbfb8aa3b, v4
	v_exp_f32_e32 v23, v8
	v_pk_add_f32 v[18:19], v[18:19], v[20:21]
	v_pk_add_f32 v[20:21], v[22:23], 1.0 op_sel_hi:[1,0]
	s_nop 0
	s_nop 0
	v_rcp_f32_e32 v8, v21
	s_nop 0
	v_mul_f32_e32 v21, v4, v8
	s_nop 0
	v_rcp_f32_e32 v4, v20
	s_nop 0
	v_mul_f32_e32 v20, v0, v4
	v_pk_mul_f32 v[26:27], v[18:19], v[20:21]
	v_lshlrev_b32_e32 v0, 16, v1
	v_and_b32_e32 v1, 0xffff0000, v1
	v_lshlrev_b32_e32 v4, 16, v5
	v_and_b32_e32 v5, 0xffff0000, v5
	v_lshlrev_b32_e32 v20, 16, v9
	v_and_b32_e32 v21, 0xffff0000, v9
	v_mul_f32_e32 v8, 0xbfb8aa3b, v20
	v_pk_add_f32 v[0:1], v[0:1], v[4:5]
	v_mul_f32_e32 v4, 0xbfb8aa3b, v21
	v_exp_f32_e32 v8, v8
	v_exp_f32_e32 v9, v4
	v_pk_mul_f32 v[18:19], v[26:27], v[26:27]
	v_pk_add_f32 v[4:5], v[8:9], 1.0 op_sel_hi:[1,0]
	s_nop 0
	s_nop 0
	v_rcp_f32_e32 v8, v5
	s_nop 0
	v_mul_f32_e32 v5, v21, v8
	s_nop 0
	v_rcp_f32_e32 v8, v4
	s_nop 0
	v_mul_f32_e32 v4, v20, v8
	v_pk_mul_f32 v[4:5], v[0:1], v[4:5]
	v_lshlrev_b32_e32 v0, 16, v2
	v_and_b32_e32 v1, 0xffff0000, v2
	v_lshlrev_b32_e32 v8, 16, v6
	v_and_b32_e32 v9, 0xffff0000, v6
	v_lshlrev_b32_e32 v2, 16, v10
	v_and_b32_e32 v6, 0xffff0000, v10
	v_mul_f32_e32 v10, 0xbfb8aa3b, v2
	v_pk_add_f32 v[0:1], v[0:1], v[8:9]
	v_mul_f32_e32 v8, 0xbfb8aa3b, v6
	v_exp_f32_e32 v22, v10
	v_exp_f32_e32 v23, v8
	v_pk_mul_f32 v[20:21], v[4:5], v[4:5]
	v_pk_add_f32 v[8:9], v[22:23], 1.0 op_sel_hi:[1,0]
	s_nop 0
	s_nop 0
	v_rcp_f32_e32 v10, v9
	s_nop 0
	v_mul_f32_e32 v9, v6, v10
	s_nop 0
	v_rcp_f32_e32 v6, v8
	s_nop 0
	v_mul_f32_e32 v8, v2, v6
	v_pk_mul_f32 v[8:9], v[0:1], v[8:9]
	v_lshlrev_b32_e32 v0, 16, v3
	v_and_b32_e32 v1, 0xffff0000, v3
	v_lshlrev_b32_e32 v2, 16, v7
	v_and_b32_e32 v3, 0xffff0000, v7
	v_lshlrev_b32_e32 v10, 16, v11
	v_and_b32_e32 v11, 0xffff0000, v11
	v_mul_f32_e32 v6, 0xbfb8aa3b, v10
	v_pk_add_f32 v[0:1], v[0:1], v[2:3]
	v_mul_f32_e32 v2, 0xbfb8aa3b, v11
	v_exp_f32_e32 v6, v6
	v_exp_f32_e32 v7, v2
	v_pk_mul_f32 v[22:23], v[8:9], v[8:9]
	v_pk_add_f32 v[2:3], v[6:7], 1.0 op_sel_hi:[1,0]
	s_nop 0
	s_nop 0
	v_rcp_f32_e32 v6, v3
	s_nop 0
	v_mul_f32_e32 v3, v11, v6
	s_nop 0
	v_rcp_f32_e32 v6, v2
	s_nop 0
	v_mul_f32_e32 v2, v10, v6
	v_pk_mul_f32 v[6:7], v[0:1], v[2:3]
	v_cvt_pk_bf16_f32 v0, v26, v27
	v_cvt_pk_bf16_f32 v1, v4, v5
	v_cvt_pk_bf16_f32 v2, v8, v9
	v_cvt_pk_bf16_f32 v3, v6, v7
	global_store_dwordx4 v[16:17], v[0:3], off offset:1024
	v_pk_mul_f32 v[24:25], v[6:7], v[6:7]
	v_lshlrev_b32_e32 v26, 16, v130
	v_and_b32_e32 v27, 0xffff0000, v130
	v_lshlrev_b32_e32 v0, 16, v138
	v_lshlrev_b32_e32 v28, 16, v134
	v_and_b32_e32 v29, 0xffff0000, v134
	v_and_b32_e32 v4, 0xffff0000, v138
	v_mul_f32_e32 v8, 0xbfb8aa3b, v0
	v_exp_f32_e32 v38, v8
	v_mul_f32_e32 v8, 0xbfb8aa3b, v4
	v_exp_f32_e32 v39, v8
	v_pk_add_f32 v[26:27], v[26:27], v[28:29]
	v_pk_add_f32 v[28:29], v[38:39], 1.0 op_sel_hi:[1,0]
	s_nop 0
	s_nop 0
	v_rcp_f32_e32 v8, v29
	s_nop 0
	v_mul_f32_e32 v29, v4, v8
	s_nop 0
	v_rcp_f32_e32 v4, v28
	s_nop 0
	v_mul_f32_e32 v28, v0, v4
	v_lshlrev_b32_e32 v0, 16, v131
	v_and_b32_e32 v1, 0xffff0000, v131
	v_lshlrev_b32_e32 v4, 16, v135
	v_and_b32_e32 v5, 0xffff0000, v135
	v_lshlrev_b32_e32 v37, 16, v139
	v_and_b32_e32 v38, 0xffff0000, v139
	v_mul_f32_e32 v8, 0xbfb8aa3b, v37
	v_pk_add_f32 v[0:1], v[0:1], v[4:5]
	v_mul_f32_e32 v4, 0xbfb8aa3b, v38
	v_exp_f32_e32 v8, v8
	v_exp_f32_e32 v9, v4
	v_pk_mul_f32 v[26:27], v[26:27], v[28:29]
	v_pk_add_f32 v[4:5], v[8:9], 1.0 op_sel_hi:[1,0]
	s_nop 0
	v_pk_mul_f32 v[28:29], v[26:27], v[26:27]
	v_rcp_f32_e32 v8, v5
	s_nop 0
	v_mul_f32_e32 v5, v38, v8
	s_nop 0
	v_rcp_f32_e32 v8, v4
	s_nop 0
	v_mul_f32_e32 v4, v37, v8
	v_lshlrev_b32_e32 v8, 16, v132
	v_and_b32_e32 v9, 0xffff0000, v132
	v_lshlrev_b32_e32 v2, 16, v140
	v_lshlrev_b32_e32 v38, 16, v136
	v_and_b32_e32 v39, 0xffff0000, v136
	v_and_b32_e32 v6, 0xffff0000, v140
	v_mul_f32_e32 v10, 0xbfb8aa3b, v2
	v_exp_f32_e32 v40, v10
	v_mul_f32_e32 v10, 0xbfb8aa3b, v6
	v_exp_f32_e32 v41, v10
	v_pk_add_f32 v[8:9], v[8:9], v[38:39]
	v_pk_mul_f32 v[4:5], v[0:1], v[4:5]
	v_pk_add_f32 v[38:39], v[40:41], 1.0 op_sel_hi:[1,0]
	s_nop 0
	v_pk_mul_f32 v[0:1], v[4:5], v[4:5]
	v_rcp_f32_e32 v10, v39
	s_nop 0
	v_mul_f32_e32 v39, v6, v10
	s_nop 0
	v_rcp_f32_e32 v6, v38
	s_nop 0
	v_mul_f32_e32 v38, v2, v6
	v_lshlrev_b32_e32 v2, 16, v133
	v_and_b32_e32 v3, 0xffff0000, v133
	v_lshlrev_b32_e32 v6, 16, v137
	v_and_b32_e32 v7, 0xffff0000, v137
	v_lshlrev_b32_e32 v37, 16, v141
	v_and_b32_e32 v40, 0xffff0000, v141
	v_mul_f32_e32 v10, 0xbfb8aa3b, v37
	v_pk_add_f32 v[2:3], v[2:3], v[6:7]
	v_mul_f32_e32 v6, 0xbfb8aa3b, v40
	v_exp_f32_e32 v10, v10
	v_exp_f32_e32 v11, v6
	v_pk_mul_f32 v[8:9], v[8:9], v[38:39]
	v_pk_add_f32 v[6:7], v[10:11], 1.0 op_sel_hi:[1,0]
	s_nop 0
	v_pk_mul_f32 v[38:39], v[8:9], v[8:9]
	v_rcp_f32_e32 v10, v7
	s_nop 0
	v_mul_f32_e32 v7, v40, v10
	s_nop 0
	v_rcp_f32_e32 v10, v6
	s_nop 0
	v_mul_f32_e32 v6, v37, v10
	v_add_f32_e32 v10, v18, v19
	v_add_f32_e32 v10, v20, v10
	v_add_f32_e32 v10, v21, v10
	v_add_f32_e32 v10, v22, v10
	v_add_f32_e32 v10, v23, v10
	v_add_f32_e32 v10, v24, v10
	v_add_f32_e32 v10, v25, v10
	v_add_f32_e32 v10, v28, v10
	v_add_f32_e32 v10, v29, v10
	v_add_f32_e32 v0, v0, v10
	v_add_f32_e32 v0, v1, v0
	v_pk_mul_f32 v[6:7], v[2:3], v[6:7]
	v_add_f32_e32 v0, v38, v0
	v_pk_mul_f32 v[2:3], v[6:7], v[6:7]
	v_add_f32_e32 v0, v39, v0
	v_add_f32_e32 v0, v2, v0
	v_add_f32_e32 v10, v3, v0
	v_cvt_pk_bf16_f32 v0, v26, v27
	v_cvt_pk_bf16_f32 v1, v4, v5
	v_cvt_pk_bf16_f32 v2, v8, v9
	v_cvt_pk_bf16_f32 v3, v6, v7
	global_store_dwordx4 v[16:17], v[0:3], off offset:2048
	ds_bpermute_b32 v0, v31, v10
	s_waitcnt lgkmcnt(0)
	v_add_f32_e32 v0, v10, v0
	ds_bpermute_b32 v1, v32, v0
	s_waitcnt lgkmcnt(0)
	v_add_f32_e32 v0, v0, v1
	ds_bpermute_b32 v1, v33, v0
	s_waitcnt lgkmcnt(0)
	v_add_f32_e32 v0, v0, v1
	ds_bpermute_b32 v1, v34, v0
	s_waitcnt lgkmcnt(0)
	v_add_f32_e32 v0, v0, v1
	ds_bpermute_b32 v1, v35, v0
	s_waitcnt lgkmcnt(0)
	v_add_f32_e32 v0, v0, v1
	ds_bpermute_b32 v1, v36, v0
	s_and_saveexec_b64 s[10:11], s[4:5]
	s_cbranch_execz .LBB0_1730
	s_waitcnt lgkmcnt(0)
	v_add_f32_e32 v0, v0, v1
	v_fmamk_f32 v0, v0, 0x3a800000, v206
	v_mul_f32_e32 v1, 0x4b800000, v0
	v_cmp_gt_f32_e32 vcc, s83, v0
	s_nop 1
	s_nop 0
	v_cndmask_b32_e32 v0, v0, v1, vcc
	v_rsq_f32_e32 v0, v0
	s_nop 0
	v_mul_f32_e32 v1, 0x45800000, v0
	v_cndmask_b32_e32 v0, v0, v1, vcc
	global_store_dword v[12:13], v0, off
	s_branch .LBB0_1730
